# job3 loop QK: 4-deep LDS operand prefetch (v[146:153] recycled as fourth buffer)
# baseline (speedup 1.0000x reference)
.LBB0_939:
	s_add_i32 s12, s11, 0xffffff80
	v_add_u32_e32 v205, v226, v204
	v_cmp_lt_i32_e32 vcc, s12, v227
	s_waitcnt lgkmcnt(0)
	s_barrier
	s_waitcnt vmcnt(7)
	ds_write_b128 v205, v[166:169]
	s_waitcnt vmcnt(6)
	ds_write_b128 v205, v[170:173] offset:9472
	s_waitcnt vmcnt(5)
	ds_write_b128 v205, v[174:177] offset:18944
	s_waitcnt vmcnt(4)
	ds_write_b128 v205, v[178:181] offset:28416
	s_waitcnt vmcnt(3)
	ds_write_b128 v205, v[182:185] offset:37888
	s_waitcnt vmcnt(2)
	ds_write_b128 v205, v[186:189] offset:47360
	s_waitcnt vmcnt(1)
	ds_write_b128 v205, v[190:193] offset:56832
	s_waitcnt vmcnt(0)
	ds_write_b128 v228, v[194:197]
	s_and_saveexec_b64 s[6:7], vcc
	v_add_u32_e32 v148, v225, v210
	ds_write_b128 v148, v[162:165] offset:512
	s_or_b64 exec, exec, s[6:7]
	s_add_u32 s60, s34, 0x16d10000
	s_addc_u32 s61, s35, 0
	s_waitcnt lgkmcnt(0)
	s_barrier
	s_cmp_ge_i32 s12, s10
	s_cbranch_scc1 .LBB0_947
	v_add_u32_e32 v229, v224, v198
	ds_read_b128 v[130:133], v229
	ds_read_b128 v[134:137], v223
	ds_read_b128 v[146:149], v229 offset:32
	ds_read_b128 v[150:153], v223 offset:1024
	ds_read_b128 v[232:235], v229 offset:64
	ds_read_b128 v[236:239], v223 offset:2048
	ds_read_b128 v[240:243], v229 offset:96
	ds_read_b128 v[246:249], v223 offset:3072
	ds_read_b128 v[154:157], v229 offset:128
	ds_read_b128 v[158:161], v223 offset:4096
	s_waitcnt lgkmcnt(8)
	v_mfma_f32_32x32x16_bf16 v[130:145], v[130:133], v[134:137], 0
	v_lshl_add_u64 v[250:251], s[60:61], 0, v[214:215]
	global_load_dwordx4 v[166:169], v[250:251], off
	s_add_u32 s60, s60, s24
	s_addc_u32 s61, s61, s25
	s_waitcnt lgkmcnt(6)
	v_mfma_f32_32x32x16_bf16 v[130:145], v[146:149], v[150:153], v[130:145]
	ds_read_b128 v[146:149], v229 offset:160
	ds_read_b128 v[150:153], v223 offset:5120
	s_waitcnt lgkmcnt(6)
	v_mfma_f32_32x32x16_bf16 v[130:145], v[232:235], v[236:239], v[130:145]
	ds_read_b128 v[232:235], v229 offset:192
	ds_read_b128 v[236:239], v223 offset:6144
	v_lshl_add_u64 v[252:253], s[60:61], 0, v[214:215]
	global_load_dwordx4 v[170:173], v[252:253], off
	s_add_u32 s60, s60, s24
	s_addc_u32 s61, s61, s25
	s_waitcnt lgkmcnt(6)
	v_mfma_f32_32x32x16_bf16 v[130:145], v[240:243], v[246:249], v[130:145]
	ds_read_b128 v[240:243], v229 offset:224
	ds_read_b128 v[246:249], v223 offset:7168
	s_waitcnt lgkmcnt(6)
	v_mfma_f32_32x32x16_bf16 v[130:145], v[154:157], v[158:161], v[130:145]
	ds_read_b128 v[154:157], v229 offset:256
	ds_read_b128 v[158:161], v223 offset:8192
	v_lshl_add_u64 v[250:251], s[60:61], 0, v[214:215]
	global_load_dwordx4 v[174:177], v[250:251], off
	s_add_u32 s60, s60, s24
	s_addc_u32 s61, s61, s25
	s_waitcnt lgkmcnt(6)
	v_mfma_f32_32x32x16_bf16 v[130:145], v[146:149], v[150:153], v[130:145]
	ds_read_b128 v[146:149], v229 offset:288
	ds_read_b128 v[150:153], v223 offset:9216
	s_waitcnt lgkmcnt(6)
	v_mfma_f32_32x32x16_bf16 v[130:145], v[232:235], v[236:239], v[130:145]
	ds_read_b128 v[232:235], v229 offset:320
	ds_read_b128 v[236:239], v223 offset:10240
	v_lshl_add_u64 v[252:253], s[60:61], 0, v[214:215]
	global_load_dwordx4 v[178:181], v[252:253], off
	s_add_u32 s60, s60, s24
	s_addc_u32 s61, s61, s25
	s_waitcnt lgkmcnt(6)
	v_mfma_f32_32x32x16_bf16 v[130:145], v[240:243], v[246:249], v[130:145]
	ds_read_b128 v[240:243], v229 offset:352
	ds_read_b128 v[246:249], v223 offset:11264
	s_waitcnt lgkmcnt(6)
	v_mfma_f32_32x32x16_bf16 v[130:145], v[154:157], v[158:161], v[130:145]
	ds_read_b128 v[154:157], v229 offset:384
	ds_read_b128 v[158:161], v223 offset:12288
	v_lshl_add_u64 v[250:251], s[60:61], 0, v[214:215]
	global_load_dwordx4 v[182:185], v[250:251], off
	s_add_u32 s60, s60, s24
	s_addc_u32 s61, s61, s25
	s_waitcnt lgkmcnt(6)
	v_mfma_f32_32x32x16_bf16 v[130:145], v[146:149], v[150:153], v[130:145]
	ds_read_b128 v[146:149], v229 offset:416
	ds_read_b128 v[150:153], v223 offset:13312
	s_waitcnt lgkmcnt(6)
	v_mfma_f32_32x32x16_bf16 v[130:145], v[232:235], v[236:239], v[130:145]
	ds_read_b128 v[232:235], v229 offset:448
	ds_read_b128 v[236:239], v223 offset:14336
	v_lshl_add_u64 v[252:253], s[60:61], 0, v[214:215]
	global_load_dwordx4 v[186:189], v[252:253], off
	s_add_u32 s60, s60, s24
	s_addc_u32 s61, s61, s25
	s_waitcnt lgkmcnt(6)
	v_mfma_f32_32x32x16_bf16 v[130:145], v[240:243], v[246:249], v[130:145]
	ds_read_b128 v[240:243], v229 offset:480
	ds_read_b128 v[246:249], v223 offset:15360
	s_waitcnt lgkmcnt(6)
	v_mfma_f32_32x32x16_bf16 v[130:145], v[154:157], v[158:161], v[130:145]
	ds_read_b128 v[154:157], v229 offset:512
	ds_read_b128 v[158:161], v223 offset:16384
	v_lshl_add_u64 v[250:251], s[60:61], 0, v[214:215]
	global_load_dwordx4 v[190:193], v[250:251], off
	s_add_u32 s60, s60, s24
	s_addc_u32 s61, s61, s25
	s_waitcnt lgkmcnt(6)
	v_mfma_f32_32x32x16_bf16 v[130:145], v[146:149], v[150:153], v[130:145]
	ds_read_b128 v[146:149], v229 offset:544
	ds_read_b128 v[150:153], v223 offset:17408
	s_waitcnt lgkmcnt(6)
	v_mfma_f32_32x32x16_bf16 v[130:145], v[232:235], v[236:239], v[130:145]
	v_lshl_add_u64 v[252:253], s[60:61], 0, v[214:215]
	global_load_dwordx4 v[194:197], v[252:253], off
	s_waitcnt lgkmcnt(4)
	v_mfma_f32_32x32x16_bf16 v[130:145], v[240:243], v[246:249], v[130:145]
	s_waitcnt lgkmcnt(2)
	v_mfma_f32_32x32x16_bf16 v[130:145], v[154:157], v[158:161], v[130:145]
	v_cmp_lt_i32_e32 vcc, s11, v227
	v_lshl_add_u64 v[250:251], s[34:35], 0, v[212:213]
	s_and_saveexec_b64 s[6:7], vcc
	s_cbranch_execz .Lj3ld_norka
	global_load_dwordx4 v[162:165], v[250:251], off
.Lj3ld_norka:
	s_or_b64 exec, exec, s[6:7]
	s_waitcnt lgkmcnt(0)
	v_mfma_f32_32x32x16_bf16 v[130:145], v[146:149], v[150:153], v[130:145]
	s_nop 11
	v_mov_b32_e32 v146, v130
	v_mov_b32_e32 v147, v131
	v_max_f32_e32 v130, v146, v147
	v_max3_f32 v130, v130, v132, v133
	v_max3_f32 v130, v130, v134, v135
	v_max3_f32 v130, v130, v136, v137
	v_max3_f32 v130, v130, v138, v139
	v_max3_f32 v130, v130, v140, v141
	v_max3_f32 v130, v130, v142, v143
	v_max3_f32 v130, v130, v144, v145
	v_sub_f32_e32 v131, v230, v130
	v_cmp_gt_f32_e32 vcc, 0xc2200000, v131
	s_cbranch_vccnz .Llazy0_full
	ds_read_b64_tr_b16 v[232:233], v222
	ds_read_b64_tr_b16 v[234:235], v222 offset:4736
	ds_read_b64_tr_b16 v[236:237], v222 offset:64
	ds_read_b64_tr_b16 v[238:239], v222 offset:4800
	ds_read_b64_tr_b16 v[240:241], v222 offset:128
	ds_read_b64_tr_b16 v[242:243], v222 offset:4864
	ds_read_b64_tr_b16 v[246:247], v222 offset:192
	ds_read_b64_tr_b16 v[248:249], v222 offset:4928
	v_mov_b32_e32 v229, v230
	v_mov_b32_e32 v130, 1.0
	s_branch .LBB0_946
